# combo25: combo23 + pass C inter-chunk state loads batched (16 in flight, refilled as consumed) instead of 16 load-wait-MFMA steps
# baseline (speedup 1.0000x reference)
; __device__ __forceinline__ unsigned pk2(float lo, float hi) { const f32x2 v = {lo, hi}; return __builtin_bit_cast(unsigned, __builtin_convertvector(v, hwbf16x2)); }
; __device__ __forceinline__ void gla_pass_c(LAS unsigned char* ldsl, const bf16_t* __restrict__ proj, const float* __restrict__ Btab, const float* __restrict__ Gst, const float* __restrict__ gout, bf16_t* __restrict__ mixed) {
;     ...
;         { const bf16_t* qp = proj + (row0 + tl) * NIN + h * 64; const float* bp = Btab + (row0 + tl) * 256 + h * 64;
; #pragma unroll
;           for (int ks = 0; ks < 4; ++ks) { const u32x4 qw = *(const u32x4*)(qp + 16 * ks + 8 * hh); const f32x4 b0 = *(const f32x4*)(bp + 16 * ks + 8 * hh), b1 = *(const f32x4*)(bp + 16 * ks + 8 * hh + 4);
;               u32x4 w; w.x = pk2(__uint_as_float(qw[0] << 16) * 0.125f * __expf(b0[0]), __uint_as_float(qw[0] & 0xffff0000u) * 0.125f * __expf(b0[1]));
;                        w.y = pk2(__uint_as_float(qw[1] << 16) * 0.125f * __expf(b0[2]), __uint_as_float(qw[1] & 0xffff0000u) * 0.125f * __expf(b0[3]));
;                        w.z = pk2(__uint_as_float(qw[2] << 16) * 0.125f * __expf(b1[0]), __uint_as_float(qw[2] & 0xffff0000u) * 0.125f * __expf(b1[1]));
;                        w.w = pk2(__uint_as_float(qw[3] << 16) * 0.125f * __expf(b1[2]), __uint_as_float(qw[3] & 0xffff0000u) * 0.125f * __expf(b1[3]));
;               qe[ks] = __builtin_bit_cast(bf16x8, w); } }
.LBB0_876:
	v_lshrrev_b32_e32 v2, 8, v111
	s_lshl_b32 s2, s3, 5
	v_and_b32_e32 v70, 3, v2
	v_or3_b32 v2, s2, v108, v122
	v_mov_b32_e32 v3, v123
	v_lshlrev_b64 v[4:5], 12, v[2:3]
	v_lshlrev_b64 v[2:3], 10, v[2:3]
	v_lshlrev_b32_e32 v124, 7, v1
	v_mov_b32_e32 v125, v161
	v_lshl_add_u64 v[4:5], s[60:61], 0, v[4:5]
	v_lshl_add_u64 v[2:3], s[58:59], 0, v[2:3]
	v_lshl_add_u64 v[4:5], v[4:5], 0, v[124:125]
	v_lshl_add_u64 v[6:7], v[2:3], 0, v[160:161]
	v_lshlrev_b32_e32 v160, 1, v112
	v_lshl_add_u64 v[2:3], v[4:5], 0, v[160:161]
	v_lshlrev_b32_e32 v160, 2, v112
	v_lshl_add_u64 v[4:5], v[6:7], 0, v[160:161]
	global_load_dwordx4 v[6:9], v[2:3], off
	global_load_dwordx4 v[10:13], v[4:5], off offset:16
	global_load_dwordx4 v[14:17], v[4:5], off
	s_mov_b32 s42, 0x3e000000
	s_movk_i32 s33, 0x2000
	v_mov_b32_e32 v67, v161
	v_lshl_add_u64 v[64:65], v[108:109], 0, v[64:65]
	v_lshl_add_u64 v[64:65], v[64:65], 0, v[66:67]
	v_lshlrev_b64 v[66:67], 12, v[64:65]
	v_lshlrev_b64 v[64:65], 10, v[64:65]
	v_lshl_or_b32 v66, v70, 7, v66
	v_lshl_or_b32 v64, v70, 8, v64
	s_sub_i32 s3, 0, s3
	v_lshl_add_u64 v[126:127], v[116:117], 0, v[66:67]
	v_lshl_add_u64 v[128:129], v[118:119], 0, v[64:65]
	v_mov_b32_e32 v121, v139
	s_waitcnt vmcnt(2)
	v_lshlrev_b32_e32 v18, 16, v6
	v_and_b32_e32 v19, 0xffff0000, v6
	s_waitcnt vmcnt(0)
	v_mul_f32_e32 v1, 0x3fb8aa3b, v14
	v_exp_f32_e32 v14, v1
	v_mul_f32_e32 v1, 0x3fb8aa3b, v15
	v_exp_f32_e32 v15, v1
	v_pk_mul_f32 v[18:19], v[18:19], s[42:43] op_sel_hi:[1,0]
	v_mul_f32_e32 v1, 0x3fb8aa3b, v16
	v_lshlrev_b32_e32 v6, 16, v7
	v_pk_mul_f32 v[14:15], v[18:19], v[14:15]
	v_and_b32_e32 v7, 0xffff0000, v7
	v_cvt_pk_bf16_f32 v80, v14, v15
	v_exp_f32_e32 v14, v1
	v_mul_f32_e32 v1, 0x3fb8aa3b, v17
	v_exp_f32_e32 v15, v1
	v_pk_mul_f32 v[6:7], v[6:7], s[42:43] op_sel_hi:[1,0]
	v_mul_f32_e32 v1, 0x3fb8aa3b, v10
	v_lshlrev_b32_e32 v10, 16, v8
	v_pk_mul_f32 v[6:7], v[6:7], v[14:15]
	s_nop 0
	v_cvt_pk_bf16_f32 v81, v6, v7
	v_exp_f32_e32 v6, v1
	v_mul_f32_e32 v1, 0x3fb8aa3b, v11
	v_exp_f32_e32 v7, v1
	v_and_b32_e32 v11, 0xffff0000, v8
	v_pk_mul_f32 v[10:11], v[10:11], s[42:43] op_sel_hi:[1,0]
	v_mul_f32_e32 v1, 0x3fb8aa3b, v12
	v_pk_mul_f32 v[6:7], v[10:11], v[6:7]
	v_lshlrev_b32_e32 v8, 16, v9
	v_cvt_pk_bf16_f32 v82, v6, v7
	v_exp_f32_e32 v6, v1
	v_mul_f32_e32 v1, 0x3fb8aa3b, v13
	v_exp_f32_e32 v7, v1
	v_and_b32_e32 v9, 0xffff0000, v9
	v_pk_mul_f32 v[8:9], v[8:9], s[42:43] op_sel_hi:[1,0]
	s_nop 0
	v_pk_mul_f32 v[6:7], v[8:9], v[6:7]
	s_nop 0
	v_cvt_pk_bf16_f32 v83, v6, v7
	global_load_dwordx4 v[6:9], v[2:3], off offset:32
	global_load_dwordx4 v[10:13], v[4:5], off offset:80
	global_load_dwordx4 v[14:17], v[4:5], off offset:64
	s_waitcnt vmcnt(2)
	v_lshlrev_b32_e32 v18, 16, v6
	v_and_b32_e32 v19, 0xffff0000, v6
	s_waitcnt vmcnt(0)
	v_mul_f32_e32 v1, 0x3fb8aa3b, v14
	v_exp_f32_e32 v14, v1
	v_mul_f32_e32 v1, 0x3fb8aa3b, v15
	v_exp_f32_e32 v15, v1
	v_pk_mul_f32 v[18:19], v[18:19], s[42:43] op_sel_hi:[1,0]
	v_mul_f32_e32 v1, 0x3fb8aa3b, v16
	v_lshlrev_b32_e32 v6, 16, v7
	v_pk_mul_f32 v[14:15], v[18:19], v[14:15]
	v_and_b32_e32 v7, 0xffff0000, v7
	v_cvt_pk_bf16_f32 v84, v14, v15
	v_exp_f32_e32 v14, v1
	v_mul_f32_e32 v1, 0x3fb8aa3b, v17
	v_exp_f32_e32 v15, v1
	v_pk_mul_f32 v[6:7], v[6:7], s[42:43] op_sel_hi:[1,0]
	v_mul_f32_e32 v1, 0x3fb8aa3b, v10
	v_lshlrev_b32_e32 v10, 16, v8
	v_pk_mul_f32 v[6:7], v[6:7], v[14:15]
	s_nop 0
	v_cvt_pk_bf16_f32 v85, v6, v7
	v_exp_f32_e32 v6, v1
	v_mul_f32_e32 v1, 0x3fb8aa3b, v11
	v_exp_f32_e32 v7, v1
	v_and_b32_e32 v11, 0xffff0000, v8
	v_pk_mul_f32 v[10:11], v[10:11], s[42:43] op_sel_hi:[1,0]
	v_mul_f32_e32 v1, 0x3fb8aa3b, v12
	v_pk_mul_f32 v[6:7], v[10:11], v[6:7]
	v_lshlrev_b32_e32 v8, 16, v9
	v_cvt_pk_bf16_f32 v86, v6, v7
	v_exp_f32_e32 v6, v1
	v_mul_f32_e32 v1, 0x3fb8aa3b, v13
	v_exp_f32_e32 v7, v1
	v_and_b32_e32 v9, 0xffff0000, v9
	v_pk_mul_f32 v[8:9], v[8:9], s[42:43] op_sel_hi:[1,0]
	s_nop 0
	v_pk_mul_f32 v[6:7], v[8:9], v[6:7]
	s_nop 0
	v_cvt_pk_bf16_f32 v87, v6, v7
	global_load_dwordx4 v[6:9], v[2:3], off offset:64
	global_load_dwordx4 v[10:13], v[4:5], off offset:144
	global_load_dwordx4 v[14:17], v[4:5], off offset:128
	s_waitcnt vmcnt(2)
	v_lshlrev_b32_e32 v18, 16, v6
	v_and_b32_e32 v19, 0xffff0000, v6
	s_waitcnt vmcnt(0)
	v_mul_f32_e32 v1, 0x3fb8aa3b, v14
	v_exp_f32_e32 v14, v1
	v_mul_f32_e32 v1, 0x3fb8aa3b, v15
	v_exp_f32_e32 v15, v1
	v_pk_mul_f32 v[18:19], v[18:19], s[42:43] op_sel_hi:[1,0]
	v_mul_f32_e32 v1, 0x3fb8aa3b, v16
	v_lshlrev_b32_e32 v6, 16, v7
	v_pk_mul_f32 v[14:15], v[18:19], v[14:15]
	v_and_b32_e32 v7, 0xffff0000, v7
	v_cvt_pk_bf16_f32 v88, v14, v15
	v_exp_f32_e32 v14, v1
	v_mul_f32_e32 v1, 0x3fb8aa3b, v17
	v_exp_f32_e32 v15, v1
	v_pk_mul_f32 v[6:7], v[6:7], s[42:43] op_sel_hi:[1,0]
	v_mul_f32_e32 v1, 0x3fb8aa3b, v10
	v_lshlrev_b32_e32 v10, 16, v8
	v_pk_mul_f32 v[6:7], v[6:7], v[14:15]
	s_nop 0
	v_cvt_pk_bf16_f32 v89, v6, v7
	v_exp_f32_e32 v6, v1
	v_mul_f32_e32 v1, 0x3fb8aa3b, v11
	v_exp_f32_e32 v7, v1
	v_and_b32_e32 v11, 0xffff0000, v8
	v_pk_mul_f32 v[10:11], v[10:11], s[42:43] op_sel_hi:[1,0]
	v_mul_f32_e32 v1, 0x3fb8aa3b, v12
	v_pk_mul_f32 v[6:7], v[10:11], v[6:7]
	v_lshlrev_b32_e32 v8, 16, v9
	v_cvt_pk_bf16_f32 v90, v6, v7
	v_exp_f32_e32 v6, v1
	v_mul_f32_e32 v1, 0x3fb8aa3b, v13
	v_exp_f32_e32 v7, v1
	v_and_b32_e32 v9, 0xffff0000, v9
	v_pk_mul_f32 v[8:9], v[8:9], s[42:43] op_sel_hi:[1,0]
	s_nop 0
	v_pk_mul_f32 v[6:7], v[8:9], v[6:7]
	s_nop 0
	v_cvt_pk_bf16_f32 v91, v6, v7
	global_load_dwordx4 v[6:9], v[2:3], off offset:96
	global_load_dwordx4 v[10:13], v[4:5], off offset:208
	s_nop 0
	global_load_dwordx4 v[2:5], v[4:5], off offset:192
	s_waitcnt vmcnt(2)
; __device__ __forceinline__ unsigned pk2(float lo, float hi) { const f32x2 v = {lo, hi}; return __builtin_bit_cast(unsigned, __builtin_convertvector(v, hwbf16x2)); }
; __device__ __forceinline__ void gla_pass_c(LAS unsigned char* ldsl, const bf16_t* __restrict__ proj, const float* __restrict__ Btab, const float* __restrict__ Gst, const float* __restrict__ gout, bf16_t* __restrict__ mixed) {
;     ...
;           for (int ks = 0; ks < 4; ++ks) { const u32x4 qw = *(const u32x4*)(qp + 16 * ks + 8 * hh); const f32x4 b0 = *(const f32x4*)(bp + 16 * ks + 8 * hh), b1 = *(const f32x4*)(bp + 16 * ks + 8 * hh + 4);
;               u32x4 w; w.x = pk2(__uint_as_float(qw[0] << 16) * 0.125f * __expf(b0[0]), __uint_as_float(qw[0] & 0xffff0000u) * 0.125f * __expf(b0[1]));
;                        w.y = pk2(__uint_as_float(qw[1] << 16) * 0.125f * __expf(b0[2]), __uint_as_float(qw[1] & 0xffff0000u) * 0.125f * __expf(b0[3]));
;                        w.z = pk2(__uint_as_float(qw[2] << 16) * 0.125f * __expf(b1[0]), __uint_as_float(qw[2] & 0xffff0000u) * 0.125f * __expf(b1[1]));
;                        w.w = pk2(__uint_as_float(qw[3] << 16) * 0.125f * __expf(b1[2]), __uint_as_float(qw[3] & 0xffff0000u) * 0.125f * __expf(b1[3]));
;               qe[ks] = __builtin_bit_cast(bf16x8, w); } }
;         f32x16 o[4] = {};
; #pragma unroll
;         for (int dvb = 0; dvb < 4; ++dvb) { const float* sp = Gst + ((size_t)item * 128 + 32 * dvb + r) * 64;
; #pragma unroll
;           for (int ks = 0; ks < 4; ++ks) { const f32x4 s0 = *(const f32x4*)(sp + 16 * ks + 8 * hh), s1 = *(const f32x4*)(sp + 16 * ks + 8 * hh + 4);
;               u32x4 sw; sw.x = pk2(s0[0], s0[1]); sw.y = pk2(s0[2], s0[3]); sw.z = pk2(s1[0], s1[1]); sw.w = pk2(s1[2], s1[3]);
;               o[dvb] = __builtin_amdgcn_mfma_f32_32x32x16_bf16(qe[ks], __builtin_bit_cast(bf16x8, sw), o[dvb], 0, 0, 0); } }
	v_lshlrev_b32_e32 v14, 16, v6
	v_and_b32_e32 v15, 0xffff0000, v6
	s_waitcnt vmcnt(0)
	v_mul_f32_e32 v1, 0x3fb8aa3b, v2
	v_exp_f32_e32 v2, v1
	v_mul_f32_e32 v1, 0x3fb8aa3b, v3
	v_exp_f32_e32 v3, v1
	v_pk_mul_f32 v[14:15], v[14:15], s[42:43] op_sel_hi:[1,0]
	v_mul_f32_e32 v1, 0x3fb8aa3b, v4
	v_lshlrev_b32_e32 v4, 16, v7
	v_pk_mul_f32 v[2:3], v[14:15], v[2:3]
	s_nop 0
	v_cvt_pk_bf16_f32 v92, v2, v3
	v_exp_f32_e32 v2, v1
	v_mul_f32_e32 v1, 0x3fb8aa3b, v5
	v_exp_f32_e32 v3, v1
	v_and_b32_e32 v5, 0xffff0000, v7
	v_pk_mul_f32 v[4:5], v[4:5], s[42:43] op_sel_hi:[1,0]
	v_mul_f32_e32 v1, 0x3fb8aa3b, v10
	v_pk_mul_f32 v[2:3], v[4:5], v[2:3]
	v_lshlrev_b32_e32 v4, 16, v8
	v_cvt_pk_bf16_f32 v93, v2, v3
	v_exp_f32_e32 v2, v1
	v_mul_f32_e32 v1, 0x3fb8aa3b, v11
	v_exp_f32_e32 v3, v1
	v_and_b32_e32 v5, 0xffff0000, v8
	v_pk_mul_f32 v[4:5], v[4:5], s[42:43] op_sel_hi:[1,0]
	v_mul_f32_e32 v1, 0x3fb8aa3b, v12
	v_pk_mul_f32 v[2:3], v[4:5], v[2:3]
	v_lshlrev_b32_e32 v4, 16, v9
	v_cvt_pk_bf16_f32 v94, v2, v3
	v_exp_f32_e32 v2, v1
	v_mul_f32_e32 v1, 0x3fb8aa3b, v13
	v_exp_f32_e32 v3, v1
	v_and_b32_e32 v5, 0xffff0000, v9
	v_ashrrev_i32_e32 v1, 31, v0
	v_pk_mul_f32 v[4:5], v[4:5], s[42:43] op_sel_hi:[1,0]
	v_lshlrev_b64 v[0:1], 15, v[0:1]
	v_pk_mul_f32 v[2:3], v[4:5], v[2:3]
	v_lshl_add_u64 v[68:69], v[114:115], 0, v[0:1]
	v_cvt_pk_bf16_f32 v95, v2, v3
	v_lshl_add_u64 v[156:157], v[68:69], 0, s[44:45]
	s_mov_b64 s[42:43], 0x4000
	v_lshl_add_u64 v[158:159], v[68:69], 0, s[42:43]
	s_mov_b64 s[42:43], 0x6000
	v_lshl_add_u64 v[182:183], v[68:69], 0, s[42:43]
	s_movk_i32 s33, 0x6000
	s_mov_b64 s[42:43], 0x60c0
	global_load_dwordx4 v[206:209], v[68:69], off
	global_load_dwordx4 v[210:213], v[68:69], off offset:16
	global_load_dwordx4 v[214:217], v[68:69], off offset:64
	global_load_dwordx4 v[218:221], v[68:69], off offset:80
	global_load_dwordx4 v[222:225], v[68:69], off offset:128
	global_load_dwordx4 v[226:229], v[68:69], off offset:144
	global_load_dwordx4 v[230:233], v[68:69], off offset:192
	global_load_dwordx4 v[234:237], v[68:69], off offset:208
	global_load_dwordx4 v[238:241], v[156:157], off
	global_load_dwordx4 v[242:245], v[156:157], off offset:16
	global_load_dwordx4 v[246:249], v[156:157], off offset:64
	global_load_dwordx4 v[162:165], v[156:157], off offset:80
	global_load_dwordx4 v[166:169], v[156:157], off offset:128
	global_load_dwordx4 v[170:173], v[156:157], off offset:144
	global_load_dwordx4 v[174:177], v[156:157], off offset:192
	global_load_dwordx4 v[178:181], v[156:157], off offset:208
	s_waitcnt vmcnt(14)
	v_cvt_pk_bf16_f32 v148, v206, v207
	v_cvt_pk_bf16_f32 v149, v208, v209
	v_cvt_pk_bf16_f32 v150, v210, v211
	v_cvt_pk_bf16_f32 v151, v212, v213
	global_load_dwordx4 v[206:209], v[158:159], off
	global_load_dwordx4 v[210:213], v[158:159], off offset:16
	s_nop 1
	v_mfma_f32_32x32x16_bf16 v[0:15], v[80:83], v[148:151], 0
	s_waitcnt vmcnt(14)
	v_cvt_pk_bf16_f32 v152, v214, v215
	v_cvt_pk_bf16_f32 v153, v216, v217
	v_cvt_pk_bf16_f32 v154, v218, v219
	v_cvt_pk_bf16_f32 v155, v220, v221
	global_load_dwordx4 v[214:217], v[158:159], off offset:64
	global_load_dwordx4 v[218:221], v[158:159], off offset:80
	s_nop 1
	v_mfma_f32_32x32x16_bf16 v[0:15], v[84:87], v[152:155], v[0:15]
	s_waitcnt vmcnt(14)
	v_cvt_pk_bf16_f32 v148, v222, v223
	v_cvt_pk_bf16_f32 v149, v224, v225
	v_cvt_pk_bf16_f32 v150, v226, v227
	v_cvt_pk_bf16_f32 v151, v228, v229
	global_load_dwordx4 v[222:225], v[158:159], off offset:128
	global_load_dwordx4 v[226:229], v[158:159], off offset:144
	s_nop 1
	v_mfma_f32_32x32x16_bf16 v[0:15], v[88:91], v[148:151], v[0:15]
	s_waitcnt vmcnt(14)
; __device__ __forceinline__ unsigned pk2(float lo, float hi) { const f32x2 v = {lo, hi}; return __builtin_bit_cast(unsigned, __builtin_convertvector(v, hwbf16x2)); }
; __device__ __forceinline__ void gla_pass_c(LAS unsigned char* ldsl, const bf16_t* __restrict__ proj, const float* __restrict__ Btab, const float* __restrict__ Gst, const float* __restrict__ gout, bf16_t* __restrict__ mixed) {
;     ...
;         for (int dvb = 0; dvb < 4; ++dvb) { const float* sp = Gst + ((size_t)item * 128 + 32 * dvb + r) * 64;
; #pragma unroll
;           for (int ks = 0; ks < 4; ++ks) { const f32x4 s0 = *(const f32x4*)(sp + 16 * ks + 8 * hh), s1 = *(const f32x4*)(sp + 16 * ks + 8 * hh + 4);
;               u32x4 sw; sw.x = pk2(s0[0], s0[1]); sw.y = pk2(s0[2], s0[3]); sw.z = pk2(s1[0], s1[1]); sw.w = pk2(s1[2], s1[3]);
;               o[dvb] = __builtin_amdgcn_mfma_f32_32x32x16_bf16(qe[ks], __builtin_bit_cast(bf16x8, sw), o[dvb], 0, 0, 0); } }
	v_cvt_pk_bf16_f32 v152, v230, v231
	v_cvt_pk_bf16_f32 v153, v232, v233
	v_cvt_pk_bf16_f32 v154, v234, v235
	v_cvt_pk_bf16_f32 v155, v236, v237
	global_load_dwordx4 v[230:233], v[158:159], off offset:192
	global_load_dwordx4 v[234:237], v[158:159], off offset:208
	s_nop 1
	v_mfma_f32_32x32x16_bf16 v[0:15], v[92:95], v[152:155], v[0:15]
	s_waitcnt vmcnt(14)
	v_cvt_pk_bf16_f32 v148, v238, v239
	v_cvt_pk_bf16_f32 v149, v240, v241
	v_cvt_pk_bf16_f32 v150, v242, v243
	v_cvt_pk_bf16_f32 v151, v244, v245
	global_load_dwordx4 v[238:241], v[182:183], off
	global_load_dwordx4 v[242:245], v[182:183], off offset:16
	s_nop 1
	v_mfma_f32_32x32x16_bf16 v[16:31], v[80:83], v[148:151], 0
	s_waitcnt vmcnt(14)
	v_cvt_pk_bf16_f32 v152, v246, v247
	v_cvt_pk_bf16_f32 v153, v248, v249
	v_cvt_pk_bf16_f32 v154, v162, v163
	v_cvt_pk_bf16_f32 v155, v164, v165
	global_load_dwordx4 v[246:249], v[182:183], off offset:64
	global_load_dwordx4 v[162:165], v[182:183], off offset:80
	s_nop 1
	v_mfma_f32_32x32x16_bf16 v[16:31], v[84:87], v[152:155], v[16:31]
	s_waitcnt vmcnt(14)
	v_cvt_pk_bf16_f32 v148, v166, v167
	v_cvt_pk_bf16_f32 v149, v168, v169
	v_cvt_pk_bf16_f32 v150, v170, v171
	v_cvt_pk_bf16_f32 v151, v172, v173
	global_load_dwordx4 v[166:169], v[182:183], off offset:128
	global_load_dwordx4 v[170:173], v[182:183], off offset:144
	s_nop 1
	v_mfma_f32_32x32x16_bf16 v[16:31], v[88:91], v[148:151], v[16:31]
	s_waitcnt vmcnt(14)
	v_cvt_pk_bf16_f32 v152, v174, v175
	v_cvt_pk_bf16_f32 v153, v176, v177
	v_cvt_pk_bf16_f32 v154, v178, v179
	v_cvt_pk_bf16_f32 v155, v180, v181
	global_load_dwordx4 v[174:177], v[182:183], off offset:192
	global_load_dwordx4 v[178:181], v[182:183], off offset:208
	s_nop 1
	v_mfma_f32_32x32x16_bf16 v[16:31], v[92:95], v[152:155], v[16:31]
	s_waitcnt vmcnt(14)
	v_cvt_pk_bf16_f32 v148, v206, v207
	v_cvt_pk_bf16_f32 v149, v208, v209
	v_cvt_pk_bf16_f32 v150, v210, v211
	v_cvt_pk_bf16_f32 v151, v212, v213
	s_nop 1
	v_mfma_f32_32x32x16_bf16 v[48:63], v[80:83], v[148:151], 0
	s_waitcnt vmcnt(12)
	v_cvt_pk_bf16_f32 v152, v214, v215
	v_cvt_pk_bf16_f32 v153, v216, v217
	v_cvt_pk_bf16_f32 v154, v218, v219
	v_cvt_pk_bf16_f32 v155, v220, v221
	s_nop 1
	v_mfma_f32_32x32x16_bf16 v[48:63], v[84:87], v[152:155], v[48:63]
	s_waitcnt vmcnt(10)
	v_cvt_pk_bf16_f32 v148, v222, v223
	v_cvt_pk_bf16_f32 v149, v224, v225
	v_cvt_pk_bf16_f32 v150, v226, v227
	v_cvt_pk_bf16_f32 v151, v228, v229
	s_nop 1
	v_mfma_f32_32x32x16_bf16 v[48:63], v[88:91], v[148:151], v[48:63]
	s_waitcnt vmcnt(8)
	v_cvt_pk_bf16_f32 v152, v230, v231
	v_cvt_pk_bf16_f32 v153, v232, v233
	v_cvt_pk_bf16_f32 v154, v234, v235
	v_cvt_pk_bf16_f32 v155, v236, v237
	s_nop 1
	v_mfma_f32_32x32x16_bf16 v[48:63], v[92:95], v[152:155], v[48:63]
	s_waitcnt vmcnt(6)
	v_cvt_pk_bf16_f32 v148, v238, v239
	v_cvt_pk_bf16_f32 v149, v240, v241
	v_cvt_pk_bf16_f32 v150, v242, v243
	v_cvt_pk_bf16_f32 v151, v244, v245
	s_nop 1
	v_mfma_f32_32x32x16_bf16 v[32:47], v[80:83], v[148:151], 0
	s_waitcnt vmcnt(4)
	v_cvt_pk_bf16_f32 v152, v246, v247
	v_cvt_pk_bf16_f32 v153, v248, v249
	v_cvt_pk_bf16_f32 v154, v162, v163
	v_cvt_pk_bf16_f32 v155, v164, v165
	s_nop 1
	v_mfma_f32_32x32x16_bf16 v[32:47], v[84:87], v[152:155], v[32:47]
	s_waitcnt vmcnt(2)
	v_cvt_pk_bf16_f32 v148, v166, v167
	v_cvt_pk_bf16_f32 v149, v168, v169
	v_cvt_pk_bf16_f32 v150, v170, v171
	v_cvt_pk_bf16_f32 v151, v172, v173
	s_nop 1
	v_mfma_f32_32x32x16_bf16 v[32:47], v[88:91], v[148:151], v[32:47]
	s_waitcnt vmcnt(0)
	v_cvt_pk_bf16_f32 v152, v174, v175
	v_cvt_pk_bf16_f32 v153, v176, v177
	v_cvt_pk_bf16_f32 v154, v178, v179
	v_cvt_pk_bf16_f32 v155, v180, v181
	s_nop 1
	v_mfma_f32_32x32x16_bf16 v[32:47], v[92:95], v[152:155], v[32:47]
	s_branch .LBB0_878
